# P11 tile boundary: 16 dead rstd2 register copies removed (the hand-written silu epilogue reads v236..v243 directly)
# baseline (speedup 1.0000x reference)
.LBB0_1320:
	v_mov_b32_e32 v143, v136
	s_lshl_b32 s27, s26, 8
	v_ashrrev_i32_e32 v128, 2, v143
	v_and_b32_e32 v128, 0xffffffc0, v128
	v_and_or_b32 v130, v143, 15, s27
	v_add_u32_e32 v148, v130, v128
	v_ashrrev_i32_e32 v149, 31, v148
	v_lshl_add_u64 v[130:131], v[148:149], 2, s[48:49]
	s_waitcnt vmcnt(0)
	s_nop 0
	s_waitcnt vmcnt(0)
	s_andn2_b64 vcc, exec, s[18:19]
	s_cbranch_vccnz .LBB0_1322
	v_mov_b32_e32 v131, v136
	v_readlane_b32 s68, v254, 4
	v_bfe_i32 v141, v131, 27, 1
	v_lshlrev_b32_e32 v135, 4, v131
	v_lshrrev_b32_e32 v141, 22, v141
	v_add_u32_e32 v141, v135, v141
	v_and_b32_e32 v141, 0xfffffc00, v141
	v_sub_u32_e32 v141, v135, v141
	v_lshrrev_b32_e32 v145, 4, v141
	v_bitop3_b32 v141, v145, v141, 32 bitop3:0x6c
	v_ashrrev_i32_e32 v139, 31, v131
	v_ashrrev_i32_e32 v147, 31, v141
	v_lshrrev_b32_e32 v139, 26, v139
	v_lshrrev_b32_e32 v147, 26, v147
	v_add_u32_e32 v139, v131, v139
	v_add_u32_e32 v147, v141, v147
	v_ashrrev_i32_e32 v139, 6, v139
	v_lshrrev_b32_e32 v149, 6, v147
	v_and_b32_e32 v147, 0xc0, v147
	v_lshlrev_b32_e32 v145, 3, v139
	v_lshlrev_b32_e32 v139, 5, v139
	v_sub_u32_e32 v141, v141, v147
	v_and_b32_e32 v145, 0x1ffff0, v145
	v_and_b32_e32 v139, 32, v139
	v_ashrrev_i16_sdwa v141, v133, sext(v141) dst_sel:DWORD dst_unused:UNUSED_PAD src0_sel:DWORD src1_sel:BYTE_0
	v_add_u32_sdwa v139, v139, sext(v141) dst_sel:DWORD dst_unused:UNUSED_PAD src0_sel:DWORD src1_sel:WORD_0
	v_add_lshl_u32 v141, v149, v145, 11
	v_add_u32_e32 v135, 0x2000, v135
	v_lshl_add_u32 v139, v139, 1, v141
	v_ashrrev_i32_e32 v141, 31, v135
	v_lshrrev_b32_e32 v141, 22, v141
	v_add_u32_e32 v141, v135, v141
	v_ashrrev_i32_e32 v141, 10, v141
	v_mul_i32_i24_e32 v145, 0x400, v141
	v_sub_u32_e32 v135, v135, v145
	v_lshrrev_b32_e32 v145, 4, v135
	v_bitop3_b32 v135, v145, v135, 32 bitop3:0x6c
	s_add_u32 s40, s64, s22
	v_readlane_b32 s70, v254, 6
	v_readlane_b32 s71, v254, 7
	v_ashrrev_i32_e32 v147, 31, v135
	s_addc_u32 s41, s65, s23
	s_mov_b64 s[50:51], s[70:71]
	v_lshrrev_b32_e32 v147, 26, v147
	s_add_u32 s50, s50, s24
	v_add_u32_e32 v147, v135, v147
	v_readfirstlane_b32 s27, v131
	s_addc_u32 s51, s51, s25
	v_lshrrev_b32_e32 v149, 6, v147
	v_and_b32_e32 v147, 0xc0, v147
	s_lshl_b32 s27, s27, 4
	v_lshlrev_b32_e32 v145, 3, v141
	v_lshlrev_b32_e32 v141, 5, v141
	v_sub_u32_e32 v135, v135, v147
	s_and_b32 s27, s27, 0xfffffc00
	v_and_b32_e32 v145, 0x1ffff0, v145
	v_and_b32_e32 v141, 32, v141
	v_ashrrev_i16_sdwa v135, v133, sext(v135) dst_sel:DWORD dst_unused:UNUSED_PAD src0_sel:DWORD src1_sel:BYTE_0
	s_add_i32 s27, s27, 0
	v_add_u32_sdwa v135, v141, sext(v135) dst_sel:DWORD dst_unused:UNUSED_PAD src0_sel:DWORD src1_sel:WORD_0
	v_add_lshl_u32 v141, v149, v145, 11
	s_add_i32 m0, s27, 0x10000
	v_lshl_add_u32 v135, v135, 1, v141
	global_load_lds_dwordx4 v139, s[50:51]
	s_add_i32 m0, s27, 0x12000
	v_readlane_b32 s69, v254, 5
	global_load_lds_dwordx4 v135, s[50:51]
	s_mov_b32 m0, s27
	v_readlane_b32 s72, v254, 8
	global_load_lds_dwordx4 v139, s[40:41]
	s_add_i32 m0, s27, 0x2000
	s_add_u32 s50, s50, 0x40000
	global_load_lds_dwordx4 v135, s[40:41]
	s_addc_u32 s51, s51, 0
	s_add_i32 m0, s27, 0x14000
	v_readlane_b32 s73, v254, 9
	global_load_lds_dwordx4 v139, s[50:51]
	s_add_i32 m0, s27, 0x16000
	s_add_u32 s40, s40, 0x40000
	global_load_lds_dwordx4 v135, s[50:51]
	s_addc_u32 s41, s41, 0
	s_add_i32 m0, s27, 0x4000
	v_readlane_b32 s74, v254, 10
	global_load_lds_dwordx4 v139, s[40:41]
	s_add_i32 m0, s27, 0x6000
	v_readlane_b32 s75, v254, 11
	global_load_lds_dwordx4 v135, s[40:41]
	v_readlane_b32 s76, v254, 12
	v_readlane_b32 s77, v254, 13
	v_readlane_b32 s78, v254, 14
	v_readlane_b32 s79, v254, 15
	v_readlane_b32 s80, v254, 16
	v_readlane_b32 s81, v254, 17
	v_readlane_b32 s82, v254, 18
	v_readlane_b32 s83, v254, 19

.LBB0_1330:
	v_mov_b32_e32 v143, v136
	s_lshl_b32 s21, s26, 8
	v_ashrrev_i32_e32 v128, 2, v143
	v_and_b32_e32 v128, 0xffffffc0, v128
	v_and_or_b32 v130, v143, 15, s21
	v_add_u32_e32 v148, v130, v128
	v_ashrrev_i32_e32 v149, 31, v148
	v_lshl_add_u64 v[130:131], v[148:149], 2, s[48:49]
	s_waitcnt vmcnt(0)
	s_nop 0
	s_waitcnt vmcnt(0)
	s_andn2_b64 vcc, exec, s[18:19]
	s_cbranch_vccnz .LBB0_1307
	v_mov_b32_e32 v131, v136
	v_readlane_b32 s68, v254, 4
	v_bfe_i32 v141, v131, 27, 1
	v_lshlrev_b32_e32 v135, 4, v131
	v_lshrrev_b32_e32 v141, 22, v141
	v_add_u32_e32 v141, v135, v141
	v_and_b32_e32 v141, 0xfffffc00, v141
	v_sub_u32_e32 v141, v135, v141
	v_lshrrev_b32_e32 v145, 4, v141
	v_bitop3_b32 v141, v145, v141, 32 bitop3:0x6c
	v_ashrrev_i32_e32 v139, 31, v131
	v_ashrrev_i32_e32 v147, 31, v141
	v_lshrrev_b32_e32 v139, 26, v139
	v_lshrrev_b32_e32 v147, 26, v147
	v_add_u32_e32 v139, v131, v139
	v_add_u32_e32 v147, v141, v147
	v_ashrrev_i32_e32 v139, 6, v139
	v_lshrrev_b32_e32 v149, 6, v147
	v_and_b32_e32 v147, 0xc0, v147
	v_lshlrev_b32_e32 v145, 3, v139
	v_lshlrev_b32_e32 v139, 5, v139
	v_sub_u32_e32 v141, v141, v147
	v_and_b32_e32 v145, 0x1ffff0, v145
	v_and_b32_e32 v139, 32, v139
	v_ashrrev_i16_sdwa v141, v133, sext(v141) dst_sel:DWORD dst_unused:UNUSED_PAD src0_sel:DWORD src1_sel:BYTE_0
	v_add_u32_sdwa v139, v139, sext(v141) dst_sel:DWORD dst_unused:UNUSED_PAD src0_sel:DWORD src1_sel:WORD_0
	v_add_lshl_u32 v141, v149, v145, 11
	v_add_u32_e32 v135, 0x2000, v135
	v_lshl_add_u32 v139, v139, 1, v141
	v_ashrrev_i32_e32 v141, 31, v135
	v_lshrrev_b32_e32 v141, 22, v141
	v_add_u32_e32 v141, v135, v141
	v_ashrrev_i32_e32 v141, 10, v141
	v_mul_i32_i24_e32 v145, 0x400, v141
	v_sub_u32_e32 v135, v135, v145
	v_lshrrev_b32_e32 v145, 4, v135
	v_bitop3_b32 v135, v145, v135, 32 bitop3:0x6c
	s_add_u32 s22, s64, s22
	v_readlane_b32 s70, v254, 6
	v_readlane_b32 s71, v254, 7
	v_ashrrev_i32_e32 v147, 31, v135
	s_addc_u32 s23, s65, s23
	s_mov_b64 s[50:51], s[70:71]
	v_lshrrev_b32_e32 v147, 26, v147
	s_add_u32 s24, s50, s24
	v_add_u32_e32 v147, v135, v147
	v_readfirstlane_b32 s21, v131
	s_addc_u32 s25, s51, s25
	v_lshrrev_b32_e32 v149, 6, v147
	v_and_b32_e32 v147, 0xc0, v147
	s_lshl_b32 s21, s21, 4
	v_lshlrev_b32_e32 v145, 3, v141
	v_lshlrev_b32_e32 v141, 5, v141
	v_sub_u32_e32 v135, v135, v147
	s_and_b32 s21, s21, 0xfffffc00
	v_and_b32_e32 v145, 0x1ffff0, v145
	v_and_b32_e32 v141, 32, v141
	v_ashrrev_i16_sdwa v135, v133, sext(v135) dst_sel:DWORD dst_unused:UNUSED_PAD src0_sel:DWORD src1_sel:BYTE_0
	s_add_i32 s21, s21, 0
	v_add_u32_sdwa v135, v141, sext(v135) dst_sel:DWORD dst_unused:UNUSED_PAD src0_sel:DWORD src1_sel:WORD_0
	v_add_lshl_u32 v141, v149, v145, 11
	s_add_i32 m0, s21, 0x10000
	v_lshl_add_u32 v135, v135, 1, v141
	global_load_lds_dwordx4 v139, s[24:25]
	s_add_i32 m0, s21, 0x12000
	v_readlane_b32 s69, v254, 5
	global_load_lds_dwordx4 v135, s[24:25]
	s_mov_b32 m0, s21
	v_readlane_b32 s72, v254, 8
	global_load_lds_dwordx4 v139, s[22:23]
	s_add_i32 m0, s21, 0x2000
	s_add_u32 s24, s24, 0x40000
	global_load_lds_dwordx4 v135, s[22:23]
	s_addc_u32 s25, s25, 0
	s_add_i32 m0, s21, 0x14000
	v_readlane_b32 s73, v254, 9
	global_load_lds_dwordx4 v139, s[24:25]
	s_add_i32 m0, s21, 0x16000
	s_add_u32 s22, s22, 0x40000
	global_load_lds_dwordx4 v135, s[24:25]
	s_addc_u32 s23, s23, 0
	s_add_i32 m0, s21, 0x4000
	v_readlane_b32 s74, v254, 10
	global_load_lds_dwordx4 v139, s[22:23]
	s_add_i32 m0, s21, 0x6000
	v_readlane_b32 s75, v254, 11
	global_load_lds_dwordx4 v135, s[22:23]
	v_readlane_b32 s76, v254, 12
	v_readlane_b32 s77, v254, 13
	v_readlane_b32 s78, v254, 14
	v_readlane_b32 s79, v254, 15
	v_readlane_b32 s80, v254, 16
	v_readlane_b32 s81, v254, 17
	v_readlane_b32 s82, v254, 18
	v_readlane_b32 s83, v254, 19
	s_branch .LBB0_1307
